# main residual GEMM epilogue: the eight exec-masked sum-of-squares dword stores per wave merged into two full-wave stores (row sums selected per fq lane group)
# speedup vs baseline: 1.0135x; 1.0016x over previous
; __device__ __forceinline__ unsigned cvt_pk_bf16(float lo, float hi) { const f32x2 v = {lo, hi}; const bf16x2_t b = __builtin_convertvector(v, bf16x2_t); return __builtin_bit_cast(unsigned, b); }
;     __device__ __forceinline__ void operator()(const f32x4 (&acc)[2][2][4][2], const pg8::Unit& u, int ui, int wr, int wc, int fr, int fq) const {
;         const int col0 = u.pn * 256 + wc * 32 + 8 * fq;
; #pragma unroll
;         for (int ai = 0; ai < 2; ++ai)
; #pragma unroll
;             for (int m = 0; m < 4; ++m) {
;                 const int row = u.pm * 256 + ai * 128 + wr * 64 + m * 16 + fr;
;                 float ss = 0.f;
; #pragma unroll
;                 for (int bj = 0; bj < 2; ++bj) {
;                     const size_t off = (size_t)row * D + col0 + bj * 128;
;                     const f32x4 o0 = acc[ai][bj][m][0], o1 = acc[ai][bj][m][1];
;                     if (OUT_F32) { *(f32x4*)(out32 + off) = o0; *(f32x4*)(out32 + off + 4) = o1; }
;                     else {
;                         ss += (o0[0] * o0[0] + o0[1] * o0[1]) + (o0[2] * o0[2] + o0[3] * o0[3]) + (o1[0] * o1[0] + o1[1] * o1[1]) + (o1[2] * o1[2] + o1[3] * o1[3]);
;                         u32x4 w; w.x = cvt_pk_bf16(o0[0], o0[1]); w.y = cvt_pk_bf16(o0[2], o0[3]); w.z = cvt_pk_bf16(o1[0], o1[1]); w.w = cvt_pk_bf16(o1[2], o1[3]);
;                         *(u32x4*)(xb + off) = w; }
;                 }
;                 if (!OUT_F32) { ss += __shfl_xor(ss, 16); ss += __shfl_xor(ss, 32);
;                     if (fq == 0) ssqp[(size_t)row * 16 + u.pn * 4 + wc] = ss; }
.Lres_noinit:
	v_mbcnt_lo_u32_b32 v247, -1, 0
	v_mbcnt_hi_u32_b32 v247, -1, v247
	v_lshrrev_b32_e32 v247, 4, v247
	v_mul_f32_e32 v151, v115, v115
	v_mul_f32_e32 v154, v117, v117
	v_fmac_f32_e32 v151, v114, v114
	v_fmac_f32_e32 v154, v116, v116
	v_add_f32_e32 v151, v151, v154
	v_mul_f32_e32 v154, v119, v119
	v_fmac_f32_e32 v154, v118, v118
	v_cvt_pk_bf16_f32 v114, v114, v115
	v_cvt_pk_bf16_f32 v115, v116, v117
	v_cvt_pk_bf16_f32 v116, v118, v119
	v_mul_f32_e32 v118, v123, v123
	v_mul_f32_e32 v119, v125, v125
	v_fmac_f32_e32 v118, v122, v122
	v_fmac_f32_e32 v119, v124, v124
	v_and_b32_e32 v149, 64, v214
	v_add_f32_e32 v118, v118, v119
	v_mul_f32_e32 v119, v127, v127
	v_xor_b32_e32 v145, 16, v214
	v_add_u32_e32 v149, 64, v149
	v_fmac_f32_e32 v119, v126, v126
	v_cmp_lt_i32_e32 vcc, v145, v149
	v_add_f32_e32 v151, v151, v154
	v_mul_f32_e32 v154, v121, v121
	v_add_f32_e32 v118, v118, v119
	v_mul_f32_e32 v119, v129, v129
	v_cndmask_b32_e32 v145, v214, v145, vcc
	v_fmac_f32_e32 v154, v120, v120
	v_fmac_f32_e32 v119, v128, v128
	v_lshlrev_b32_e32 v150, 2, v145
	v_xor_b32_e32 v145, 32, v214
	v_add_f32_e32 v151, v154, v151
	v_add_f32_e32 v118, v119, v118
	v_cmp_lt_i32_e32 vcc, v145, v149
	v_add_f32_e32 v151, v151, v118
	v_lshl_add_u32 v144, s89, 8, v1
	v_cndmask_b32_e32 v145, v214, v145, vcc
	ds_bpermute_b32 v154, v150, v151
	v_lshlrev_b32_e32 v149, 2, v145
	v_ashrrev_i32_e32 v145, 31, v144
	v_lshl_or_b32 v142, s54, 8, v147
	v_lshlrev_b64 v[152:153], 11, v[144:145]
	v_ashrrev_i32_e32 v143, 31, v142
	v_lshl_add_u64 v[118:119], s[4:5], 0, v[152:153]
	v_cvt_pk_bf16_f32 v117, v120, v121
	v_lshl_add_u64 v[120:121], v[142:143], 1, v[118:119]
	global_store_dwordx4 v[120:121], v[114:117], off
	s_lshl_b32 s18, s54, 2
	s_ashr_i32 s19, s18, 31
	s_waitcnt lgkmcnt(0)
	v_add_f32_e32 v114, v151, v154
	ds_bpermute_b32 v115, v149, v114
	v_cvt_pk_bf16_f32 v116, v122, v123
	v_cvt_pk_bf16_f32 v117, v124, v125
	v_cvt_pk_bf16_f32 v118, v126, v127
	v_cvt_pk_bf16_f32 v119, v128, v129
	global_store_dwordx4 v[120:121], v[116:119], off offset:256
	s_waitcnt lgkmcnt(0)
	v_add_f32_e32 v246, v114, v115
	v_cmp_eq_u32_e64 s[98:99], 0, v247
	s_lshl_b32 s54, s28, 2
	s_nop 1
	v_cndmask_b32_e64 v253, v253, v246, s[98:99]
	v_mul_f32_e32 v118, v95, v95
	v_mul_f32_e32 v119, v97, v97
	v_fmac_f32_e32 v118, v94, v94
	v_fmac_f32_e32 v119, v96, v96
	v_add_f32_e32 v118, v118, v119
	v_mul_f32_e32 v119, v99, v99
	v_fmac_f32_e32 v119, v98, v98
	v_cvt_pk_bf16_f32 v94, v94, v95
	v_cvt_pk_bf16_f32 v95, v96, v97
	v_cvt_pk_bf16_f32 v96, v98, v99
	v_mul_f32_e32 v98, v103, v103
	v_mul_f32_e32 v99, v105, v105
	v_fmac_f32_e32 v98, v102, v102
	v_fmac_f32_e32 v99, v104, v104
	v_add_f32_e32 v98, v98, v99
	v_mul_f32_e32 v99, v107, v107
	v_fmac_f32_e32 v99, v106, v106
	v_add_f32_e32 v118, v118, v119
	v_mul_f32_e32 v119, v101, v101
	v_add_f32_e32 v98, v98, v99
	v_mul_f32_e32 v99, v109, v109
	v_fmac_f32_e32 v119, v100, v100
	v_fmac_f32_e32 v99, v108, v108
	v_add_f32_e32 v118, v119, v118
	v_add_f32_e32 v98, v99, v98
	v_add_f32_e32 v118, v118, v98
	v_or_b32_e32 v114, 16, v144
	ds_bpermute_b32 v119, v150, v118
	s_waitcnt lgkmcnt(0)
	v_ashrrev_i32_e32 v115, 31, v114
	v_lshlrev_b64 v[116:117], 11, v[114:115]
	v_lshl_add_u64 v[98:99], s[4:5], 0, v[116:117]
	v_cvt_pk_bf16_f32 v97, v100, v101
	v_lshl_add_u64 v[100:101], v[142:143], 1, v[98:99]
	global_store_dwordx4 v[100:101], v[94:97], off
	v_cvt_pk_bf16_f32 v98, v106, v107
	v_cvt_pk_bf16_f32 v99, v108, v109
	v_add_f32_e32 v94, v118, v119
	ds_bpermute_b32 v95, v149, v94
	v_cvt_pk_bf16_f32 v96, v102, v103
	v_cvt_pk_bf16_f32 v97, v104, v105
	global_store_dwordx4 v[100:101], v[96:99], off offset:256
	s_waitcnt lgkmcnt(0)
	v_add_f32_e32 v246, v94, v95
	v_cmp_eq_u32_e64 s[98:99], 1, v247
	s_lshl_b32 s54, s28, 2
	s_nop 1
	v_cndmask_b32_e64 v253, v253, v246, s[98:99]
	v_mul_f32_e32 v98, v63, v63
	v_mul_f32_e32 v99, v65, v65
	v_fmac_f32_e32 v98, v62, v62
	v_fmac_f32_e32 v99, v64, v64
	v_add_f32_e32 v98, v98, v99
	v_mul_f32_e32 v99, v67, v67
	v_fmac_f32_e32 v99, v66, v66
	v_cvt_pk_bf16_f32 v62, v62, v63
	v_cvt_pk_bf16_f32 v63, v64, v65
	v_cvt_pk_bf16_f32 v64, v66, v67
	v_mul_f32_e32 v66, v71, v71
	v_mul_f32_e32 v67, v73, v73
	v_fmac_f32_e32 v66, v70, v70
	v_fmac_f32_e32 v67, v72, v72
	v_add_f32_e32 v66, v66, v67
	v_mul_f32_e32 v67, v79, v79
	v_fmac_f32_e32 v67, v78, v78
	v_add_f32_e32 v98, v98, v99
	v_mul_f32_e32 v99, v69, v69
	v_add_f32_e32 v66, v66, v67
	v_mul_f32_e32 v67, v81, v81
	v_fmac_f32_e32 v99, v68, v68
	v_fmac_f32_e32 v67, v80, v80
	v_add_f32_e32 v98, v99, v98
	v_add_f32_e32 v66, v67, v66
	v_add_f32_e32 v98, v98, v66
	v_or_b32_e32 v94, 32, v144
	ds_bpermute_b32 v99, v150, v98
	s_waitcnt lgkmcnt(0)
	v_ashrrev_i32_e32 v95, 31, v94
	v_lshlrev_b64 v[96:97], 11, v[94:95]
	v_lshl_add_u64 v[66:67], s[4:5], 0, v[96:97]
	v_cvt_pk_bf16_f32 v65, v68, v69
	v_lshl_add_u64 v[68:69], v[142:143], 1, v[66:67]
	global_store_dwordx4 v[68:69], v[62:65], off
	v_cvt_pk_bf16_f32 v66, v78, v79
	v_cvt_pk_bf16_f32 v67, v80, v81
	v_add_f32_e32 v62, v98, v99
	ds_bpermute_b32 v63, v149, v62
	v_cvt_pk_bf16_f32 v64, v70, v71
	v_cvt_pk_bf16_f32 v65, v72, v73
	global_store_dwordx4 v[68:69], v[64:67], off offset:256
	s_waitcnt lgkmcnt(0)
; __device__ __forceinline__ unsigned cvt_pk_bf16(float lo, float hi) { const f32x2 v = {lo, hi}; const bf16x2_t b = __builtin_convertvector(v, bf16x2_t); return __builtin_bit_cast(unsigned, b); }
;     __device__ __forceinline__ void operator()(const f32x4 (&acc)[2][2][4][2], const pg8::Unit& u, int ui, int wr, int wc, int fr, int fq) const {
;         const int col0 = u.pn * 256 + wc * 32 + 8 * fq;
; #pragma unroll
;         for (int ai = 0; ai < 2; ++ai)
; #pragma unroll
;             for (int m = 0; m < 4; ++m) {
;                 const int row = u.pm * 256 + ai * 128 + wr * 64 + m * 16 + fr;
;                 float ss = 0.f;
; #pragma unroll
;                 for (int bj = 0; bj < 2; ++bj) {
;                     const size_t off = (size_t)row * D + col0 + bj * 128;
;                     const f32x4 o0 = acc[ai][bj][m][0], o1 = acc[ai][bj][m][1];
;                     if (OUT_F32) { *(f32x4*)(out32 + off) = o0; *(f32x4*)(out32 + off + 4) = o1; }
;                     else {
;                         ss += (o0[0] * o0[0] + o0[1] * o0[1]) + (o0[2] * o0[2] + o0[3] * o0[3]) + (o1[0] * o1[0] + o1[1] * o1[1]) + (o1[2] * o1[2] + o1[3] * o1[3]);
;                         u32x4 w; w.x = cvt_pk_bf16(o0[0], o0[1]); w.y = cvt_pk_bf16(o0[2], o0[3]); w.z = cvt_pk_bf16(o1[0], o1[1]); w.w = cvt_pk_bf16(o1[2], o1[3]);
;                         *(u32x4*)(xb + off) = w; }
;                 }
;                 if (!OUT_F32) { ss += __shfl_xor(ss, 16); ss += __shfl_xor(ss, 32);
;                     if (fq == 0) ssqp[(size_t)row * 16 + u.pn * 4 + wc] = ss; }
	v_add_f32_e32 v246, v62, v63
	v_cmp_eq_u32_e64 s[98:99], 2, v247
	s_lshl_b32 s54, s28, 2
	s_nop 1
	v_cndmask_b32_e64 v253, v253, v246, s[98:99]
	v_mul_f32_e32 v66, v23, v23
	v_mul_f32_e32 v67, v25, v25
	v_fmac_f32_e32 v66, v22, v22
	v_fmac_f32_e32 v67, v24, v24
	v_add_f32_e32 v66, v66, v67
	v_mul_f32_e32 v67, v35, v35
	v_fmac_f32_e32 v67, v34, v34
	v_cvt_pk_bf16_f32 v22, v22, v23
	v_cvt_pk_bf16_f32 v23, v24, v25
	v_cvt_pk_bf16_f32 v24, v34, v35
	v_mul_f32_e32 v34, v39, v39
	v_mul_f32_e32 v35, v41, v41
	v_fmac_f32_e32 v34, v38, v38
	v_fmac_f32_e32 v35, v40, v40
	v_add_f32_e32 v34, v34, v35
	v_mul_f32_e32 v35, v47, v47
	v_fmac_f32_e32 v35, v46, v46
	v_add_f32_e32 v66, v66, v67
	v_mul_f32_e32 v67, v37, v37
	v_add_f32_e32 v34, v34, v35
	v_mul_f32_e32 v35, v49, v49
	v_fmac_f32_e32 v67, v36, v36
	v_fmac_f32_e32 v35, v48, v48
	v_add_f32_e32 v66, v67, v66
	v_add_f32_e32 v34, v35, v34
	v_cvt_pk_bf16_f32 v25, v36, v37
	v_add_f32_e32 v36, v66, v34
	v_or_b32_e32 v62, 48, v144
	ds_bpermute_b32 v37, v150, v36
	s_waitcnt lgkmcnt(0)
	v_ashrrev_i32_e32 v63, 31, v62
	v_lshlrev_b64 v[64:65], 11, v[62:63]
	v_lshl_add_u64 v[34:35], s[4:5], 0, v[64:65]
	v_lshl_add_u64 v[64:65], v[142:143], 1, v[34:35]
	global_store_dwordx4 v[64:65], v[22:25], off
	v_cvt_pk_bf16_f32 v34, v38, v39
	v_cvt_pk_bf16_f32 v35, v40, v41
	v_add_f32_e32 v22, v36, v37
	ds_bpermute_b32 v23, v149, v22
	v_cvt_pk_bf16_f32 v36, v46, v47
	v_cvt_pk_bf16_f32 v37, v48, v49
	global_store_dwordx4 v[64:65], v[34:37], off offset:256
	s_waitcnt lgkmcnt(0)
	v_add_f32_e32 v246, v22, v23
	v_cmp_eq_u32_e64 s[98:99], 3, v247
	s_lshl_b32 s54, s28, 2
	s_nop 1
	v_cndmask_b32_e64 v253, v253, v246, s[98:99]
	v_mul_f32_e32 v34, v15, v15
	v_mul_f32_e32 v35, v17, v17
	v_fmac_f32_e32 v34, v14, v14
	v_fmac_f32_e32 v35, v16, v16
	v_add_f32_e32 v34, v34, v35
	v_mul_f32_e32 v35, v27, v27
	v_fmac_f32_e32 v35, v26, v26
	v_cvt_pk_bf16_f32 v14, v14, v15
	v_cvt_pk_bf16_f32 v15, v16, v17
	v_cvt_pk_bf16_f32 v16, v26, v27
	v_mul_f32_e32 v26, v31, v31
	v_mul_f32_e32 v27, v33, v33
	v_fmac_f32_e32 v26, v30, v30
	v_fmac_f32_e32 v27, v32, v32
	v_add_f32_e32 v26, v26, v27
	v_mul_f32_e32 v27, v111, v111
	v_fmac_f32_e32 v27, v110, v110
	v_add_f32_e32 v34, v34, v35
	v_mul_f32_e32 v35, v29, v29
	v_add_f32_e32 v26, v26, v27
	v_mul_f32_e32 v27, v113, v113
	v_fmac_f32_e32 v35, v28, v28
	v_fmac_f32_e32 v27, v112, v112
	v_add_f32_e32 v34, v35, v34
	v_add_f32_e32 v26, v27, v26
	v_add_f32_e32 v26, v34, v26
	v_add_u32_e32 v22, 0x80, v144
	ds_bpermute_b32 v27, v150, v26
	s_waitcnt lgkmcnt(0)
	v_ashrrev_i32_e32 v23, 31, v22
	v_lshlrev_b64 v[24:25], 11, v[22:23]
	v_lshl_add_u64 v[24:25], s[4:5], 0, v[24:25]
	v_cvt_pk_bf16_f32 v17, v28, v29
	v_lshl_add_u64 v[28:29], v[142:143], 1, v[24:25]
	global_store_dwordx4 v[28:29], v[14:17], off
	v_cvt_pk_bf16_f32 v24, v30, v31
	v_cvt_pk_bf16_f32 v25, v32, v33
	v_add_f32_e32 v14, v26, v27
	ds_bpermute_b32 v15, v149, v14
	v_cvt_pk_bf16_f32 v26, v110, v111
	v_cvt_pk_bf16_f32 v27, v112, v113
	global_store_dwordx4 v[28:29], v[24:27], off offset:256
	s_waitcnt lgkmcnt(0)
	v_add_f32_e32 v246, v14, v15
	v_cmp_eq_u32_e64 s[98:99], 0, v247
	s_lshl_b32 s54, s28, 2
	s_nop 1
	v_cndmask_b32_e64 v254, v254, v246, s[98:99]
	v_mul_f32_e32 v22, v75, v75
	v_mul_f32_e32 v23, v77, v77
	v_mul_f32_e32 v27, v87, v87
	v_mul_f32_e32 v28, v89, v89
	v_fmac_f32_e32 v22, v74, v74
	v_fmac_f32_e32 v23, v76, v76
	v_fmac_f32_e32 v27, v86, v86
	v_fmac_f32_e32 v28, v88, v88
	v_add_f32_e32 v22, v22, v23
	v_mul_f32_e32 v23, v83, v83
	v_add_f32_e32 v27, v27, v28
	v_mul_f32_e32 v28, v91, v91
	v_fmac_f32_e32 v23, v82, v82
	v_fmac_f32_e32 v28, v90, v90
	v_add_f32_e32 v22, v22, v23
	v_mul_f32_e32 v23, v85, v85
	v_add_f32_e32 v27, v27, v28
	v_mul_f32_e32 v28, v93, v93
	v_fmac_f32_e32 v23, v84, v84
	v_fmac_f32_e32 v28, v92, v92
	v_add_f32_e32 v26, v23, v22
	v_add_f32_e32 v27, v28, v27
	v_add_f32_e32 v28, v26, v27
	ds_bpermute_b32 v29, v150, v28
	v_add_u32_e32 v14, 0x90, v144
	s_waitcnt lgkmcnt(0)
; __device__ __forceinline__ unsigned cvt_pk_bf16(float lo, float hi) { const f32x2 v = {lo, hi}; const bf16x2_t b = __builtin_convertvector(v, bf16x2_t); return __builtin_bit_cast(unsigned, b); }
;     __device__ __forceinline__ void operator()(const f32x4 (&acc)[2][2][4][2], const pg8::Unit& u, int ui, int wr, int wc, int fr, int fq) const {
;         const int col0 = u.pn * 256 + wc * 32 + 8 * fq;
; #pragma unroll
;         for (int ai = 0; ai < 2; ++ai)
; #pragma unroll
;             for (int m = 0; m < 4; ++m) {
;                 const int row = u.pm * 256 + ai * 128 + wr * 64 + m * 16 + fr;
;                 float ss = 0.f;
; #pragma unroll
;                 for (int bj = 0; bj < 2; ++bj) {
;                     const size_t off = (size_t)row * D + col0 + bj * 128;
;                     const f32x4 o0 = acc[ai][bj][m][0], o1 = acc[ai][bj][m][1];
;                     if (OUT_F32) { *(f32x4*)(out32 + off) = o0; *(f32x4*)(out32 + off + 4) = o1; }
;                     else {
;                         ss += (o0[0] * o0[0] + o0[1] * o0[1]) + (o0[2] * o0[2] + o0[3] * o0[3]) + (o1[0] * o1[0] + o1[1] * o1[1]) + (o1[2] * o1[2] + o1[3] * o1[3]);
;                         u32x4 w; w.x = cvt_pk_bf16(o0[0], o0[1]); w.y = cvt_pk_bf16(o0[2], o0[3]); w.z = cvt_pk_bf16(o1[0], o1[1]); w.w = cvt_pk_bf16(o1[2], o1[3]);
;                         *(u32x4*)(xb + off) = w; }
;                 }
;                 if (!OUT_F32) { ss += __shfl_xor(ss, 16); ss += __shfl_xor(ss, 32);
;                     if (fq == 0) ssqp[(size_t)row * 16 + u.pn * 4 + wc] = ss; }
	v_ashrrev_i32_e32 v15, 31, v14
	v_lshlrev_b64 v[16:17], 11, v[14:15]
	v_lshl_add_u64 v[16:17], s[4:5], 0, v[16:17]
	v_lshl_add_u64 v[26:27], v[142:143], 1, v[16:17]
	v_add_f32_e32 v16, v28, v29
	ds_bpermute_b32 v17, v149, v16
	v_cvt_pk_bf16_f32 v22, v74, v75
	v_cvt_pk_bf16_f32 v23, v76, v77
	v_cvt_pk_bf16_f32 v24, v82, v83
	v_cvt_pk_bf16_f32 v25, v84, v85
	global_store_dwordx4 v[26:27], v[22:25], off
	s_nop 1
	v_cvt_pk_bf16_f32 v22, v86, v87
	v_cvt_pk_bf16_f32 v23, v88, v89
	v_cvt_pk_bf16_f32 v24, v90, v91
	v_cvt_pk_bf16_f32 v25, v92, v93
	global_store_dwordx4 v[26:27], v[22:25], off offset:256
	s_waitcnt lgkmcnt(0)
	v_add_f32_e32 v246, v16, v17
	v_cmp_eq_u32_e64 s[98:99], 1, v247
	s_lshl_b32 s54, s28, 2
	s_nop 1
	v_cndmask_b32_e64 v254, v254, v246, s[98:99]
	v_mul_f32_e32 v22, v43, v43
	v_mul_f32_e32 v23, v45, v45
	v_mul_f32_e32 v27, v55, v55
	v_mul_f32_e32 v28, v57, v57
	v_fmac_f32_e32 v22, v42, v42
	v_fmac_f32_e32 v23, v44, v44
	v_fmac_f32_e32 v27, v54, v54
	v_fmac_f32_e32 v28, v56, v56
	v_add_f32_e32 v22, v22, v23
	v_mul_f32_e32 v23, v51, v51
	v_add_f32_e32 v27, v27, v28
	v_mul_f32_e32 v28, v59, v59
	v_fmac_f32_e32 v23, v50, v50
	v_fmac_f32_e32 v28, v58, v58
	v_add_f32_e32 v22, v22, v23
	v_mul_f32_e32 v23, v53, v53
	v_add_f32_e32 v27, v27, v28
	v_mul_f32_e32 v28, v61, v61
	v_fmac_f32_e32 v23, v52, v52
	v_fmac_f32_e32 v28, v60, v60
	v_add_f32_e32 v26, v23, v22
	v_add_f32_e32 v27, v28, v27
	v_add_f32_e32 v28, v26, v27
	ds_bpermute_b32 v29, v150, v28
	v_add_u32_e32 v14, 0xa0, v144
	v_ashrrev_i32_e32 v15, 31, v14
	s_waitcnt lgkmcnt(0)
	v_lshlrev_b64 v[16:17], 11, v[14:15]
	v_lshl_add_u64 v[16:17], s[4:5], 0, v[16:17]
	v_lshl_add_u64 v[26:27], v[142:143], 1, v[16:17]
	v_add_f32_e32 v16, v28, v29
	ds_bpermute_b32 v17, v149, v16
	v_cvt_pk_bf16_f32 v22, v42, v43
	v_cvt_pk_bf16_f32 v23, v44, v45
	v_cvt_pk_bf16_f32 v24, v50, v51
	v_cvt_pk_bf16_f32 v25, v52, v53
	global_store_dwordx4 v[26:27], v[22:25], off
	s_nop 1
	v_cvt_pk_bf16_f32 v22, v54, v55
	v_cvt_pk_bf16_f32 v23, v56, v57
	v_cvt_pk_bf16_f32 v24, v58, v59
	v_cvt_pk_bf16_f32 v25, v60, v61
	global_store_dwordx4 v[26:27], v[22:25], off offset:256
	s_waitcnt lgkmcnt(0)
	v_add_f32_e32 v246, v16, v17
	v_cmp_eq_u32_e64 s[98:99], 2, v247
	s_lshl_b32 s54, s28, 2
	s_nop 1
	v_cndmask_b32_e64 v254, v254, v246, s[98:99]
	v_mul_f32_e32 v22, v3, v3
	v_mul_f32_e32 v23, v5, v5
	v_fmac_f32_e32 v22, v2, v2
	v_fmac_f32_e32 v23, v4, v4
	v_add_f32_e32 v22, v22, v23
	v_mul_f32_e32 v23, v7, v7
	v_fmac_f32_e32 v23, v6, v6
	v_cvt_pk_bf16_f32 v2, v2, v3
	v_cvt_pk_bf16_f32 v3, v4, v5
	v_cvt_pk_bf16_f32 v4, v6, v7
	v_mul_f32_e32 v6, v11, v11
	v_mul_f32_e32 v7, v13, v13
	v_fmac_f32_e32 v6, v10, v10
	v_fmac_f32_e32 v7, v12, v12
	v_add_f32_e32 v6, v6, v7
	v_mul_f32_e32 v7, v19, v19
	v_fmac_f32_e32 v7, v18, v18
	v_add_f32_e32 v22, v22, v23
	v_mul_f32_e32 v23, v9, v9
	v_add_f32_e32 v6, v6, v7
	v_mul_f32_e32 v7, v21, v21
	v_fmac_f32_e32 v23, v8, v8
	v_fmac_f32_e32 v7, v20, v20
	v_add_f32_e32 v22, v23, v22
	v_add_f32_e32 v6, v7, v6
	v_add_f32_e32 v22, v22, v6
	v_add_u32_e32 v14, 0xb0, v144
	ds_bpermute_b32 v23, v150, v22
	v_ashrrev_i32_e32 v15, 31, v14
	s_waitcnt lgkmcnt(0)
	v_lshlrev_b64 v[16:17], 11, v[14:15]
	v_lshl_add_u64 v[6:7], s[4:5], 0, v[16:17]
	v_cvt_pk_bf16_f32 v5, v8, v9
	v_lshl_add_u64 v[8:9], v[142:143], 1, v[6:7]
	global_store_dwordx4 v[8:9], v[2:5], off
	v_cvt_pk_bf16_f32 v6, v18, v19
	v_cvt_pk_bf16_f32 v7, v20, v21
	v_add_f32_e32 v2, v22, v23
	ds_bpermute_b32 v3, v149, v2
	v_cvt_pk_bf16_f32 v4, v10, v11
	v_cvt_pk_bf16_f32 v5, v12, v13
	global_store_dwordx4 v[8:9], v[4:7], off offset:256
	s_waitcnt lgkmcnt(0)
	v_add_f32_e32 v246, v2, v3
	v_cmp_eq_u32_e64 s[98:99], 3, v247
	s_lshl_b32 s54, s28, 2
	s_nop 1
	v_cndmask_b32_e64 v254, v254, v246, s[98:99]
	s_and_b64 vcc, exec, s[68:69]
	v_lshl_add_u32 v246, v247, 4, v144
	v_mov_b32_e32 v247, 0
	v_lshlrev_b64 v[246:247], 6, v[246:247]
	v_lshl_add_u64 v[246:247], s[6:7], 0, v[246:247]
	v_lshl_add_u64 v[246:247], s[18:19], 2, v[246:247]
	v_lshl_add_u64 v[246:247], v[246:247], 0, s[54:55]
	s_mov_b32 s98, 0x2000
	s_mov_b32 s99, 0
	global_store_dword v[246:247], v253, off
	v_lshl_add_u64 v[246:247], v[246:247], 0, s[98:99]
	global_store_dword v[246:247], v254, off
	s_mov_b64 s[18:19], -1
	s_cbranch_vccnz .LBB0_586
	s_waitcnt lgkmcnt(0)
	s_andn2_b64 vcc, exec, s[82:83]
	s_cbranch_vccnz .LBB0_585
	s_barrier
	s_branch .LBB0_585
